# v57 + nt cache hint on the barrier-time weight conversion loads and stores (read-once / write-once streams)
# speedup vs baseline: 1.0051x; 1.0051x over previous
.LBB0_500:
	v_and_b32_e32 v82, 56, v2
	v_and_b32_e32 v16, 63, v2
	v_or_b32_e32 v2, s12, v82
	v_mad_u64_u32 v[6:7], s[6:7], s26, v2, 0
	v_cmp_lt_i32_e64 s[6:7], -1, v3
	s_ashr_i32 s13, s12, 31
	v_mul_lo_u32 v5, s27, v2
	v_cndmask_b32_e64 v186, 0, v3, s[6:7]
	v_or_b32_e32 v3, 1, v82
	s_mul_i32 s0, s26, s13
	v_or_b32_e32 v2, s12, v3
	v_add3_u32 v7, v7, s0, v5
	v_mul_lo_u32 v5, s27, v2
	v_mad_u64_u32 v[8:9], s[38:39], s26, v2, 0
	v_add3_u32 v9, v9, s0, v5
	v_lshl_add_u64 v[6:7], v[6:7], 2, s[4:5]
	v_lshlrev_b64 v[10:11], 2, v[186:187]
	v_lshl_add_u64 v[8:9], v[8:9], 2, s[4:5]
	v_or_b32_e32 v5, 2, v82
	v_lshl_add_u64 v[6:7], v[6:7], 0, v[10:11]
	v_lshl_add_u64 v[8:9], v[8:9], 0, v[10:11]
	v_or_b32_e32 v2, s12, v5
	global_load_dwordx4 v[54:57], v[6:7], off nt
	global_load_dwordx4 v[50:53], v[8:9], off nt
	v_mul_lo_u32 v8, s27, v2
	v_mad_u64_u32 v[6:7], s[38:39], s26, v2, 0
	v_add3_u32 v7, v7, s0, v8
	v_lshl_add_u64 v[6:7], v[6:7], 2, s[4:5]
	v_lshl_add_u64 v[8:9], v[6:7], 0, v[10:11]
	v_or_b32_e32 v6, 3, v82
	v_or_b32_e32 v2, s12, v6
	v_mul_lo_u32 v7, s27, v2
	v_mad_u64_u32 v[12:13], s[38:39], s26, v2, 0
	v_add3_u32 v13, v13, s0, v7
	v_lshl_add_u64 v[12:13], v[12:13], 2, s[4:5]
	v_or_b32_e32 v7, 4, v82
	v_lshl_add_u64 v[12:13], v[12:13], 0, v[10:11]
	v_or_b32_e32 v2, s12, v7
	global_load_dwordx4 v[62:65], v[8:9], off nt
	global_load_dwordx4 v[58:61], v[12:13], off nt
	v_mul_lo_u32 v12, s27, v2
	v_mad_u64_u32 v[8:9], s[38:39], s26, v2, 0
	v_add3_u32 v9, v9, s0, v12
	v_lshl_add_u64 v[8:9], v[8:9], 2, s[4:5]
	v_lshl_add_u64 v[12:13], v[8:9], 0, v[10:11]
	v_or_b32_e32 v8, 5, v82
	v_or_b32_e32 v2, s12, v8
	v_mul_lo_u32 v9, s27, v2
	v_mad_u64_u32 v[14:15], s[38:39], s26, v2, 0
	v_add3_u32 v15, v15, s0, v9
	v_lshl_add_u64 v[14:15], v[14:15], 2, s[4:5]
	v_or_b32_e32 v9, 6, v82
	v_lshl_add_u64 v[14:15], v[14:15], 0, v[10:11]
	v_or_b32_e32 v2, s12, v9
	v_or_b32_e32 v42, 7, v16
	global_load_dwordx4 v[70:73], v[12:13], off nt
	global_load_dwordx4 v[66:69], v[14:15], off nt
	v_mul_lo_u32 v14, s27, v2
	v_mad_u64_u32 v[12:13], s[38:39], s26, v2, 0
	v_or_b32_e32 v2, s12, v42
	v_add3_u32 v13, v13, s0, v14
	v_mul_lo_u32 v16, s27, v2
	v_mad_u64_u32 v[14:15], s[26:27], s26, v2, 0
	v_lshl_add_u64 v[12:13], v[12:13], 2, s[4:5]
	v_add3_u32 v15, v15, s0, v16
	v_lshl_add_u64 v[12:13], v[12:13], 0, v[10:11]
	v_lshl_add_u64 v[14:15], v[14:15], 2, s[4:5]
	v_lshl_add_u64 v[10:11], v[14:15], 0, v[10:11]
	global_load_dwordx4 v[78:81], v[12:13], off nt
	global_load_dwordx4 v[74:77], v[10:11], off nt
	s_cmp_eq_u64 s[24:25], 0
	v_lshlrev_b32_e32 v2, 2, v82
	s_cbranch_scc1 .LBB0_502
	s_lshl_b64 s[4:5], s[12:13], 2
	s_add_u32 s4, s24, s4
	s_addc_u32 s5, s25, s5
	global_load_dwordx4 v[10:13], v2, s[4:5] nt
	global_load_dwordx4 v[14:17], v2, s[4:5] offset:16 nt
	s_branch .LBB0_503

.LBB0_503:
	v_or_b32_e32 v18, s20, v82
	s_ashr_i32 s21, s20, 31
	v_mul_lo_u32 v20, s35, v18
	v_mad_u64_u32 v[18:19], s[4:5], s34, v18, 0
	s_mul_i32 s0, s34, s21
	v_cmp_lt_i32_e64 s[4:5], -1, v4
	v_or_b32_e32 v3, s20, v3
	v_add3_u32 v19, v19, s0, v20
	v_cndmask_b32_e64 v186, 0, v4, s[4:5]
	v_mul_lo_u32 v4, s35, v3
	v_mad_u64_u32 v[20:21], s[24:25], s34, v3, 0
	v_or_b32_e32 v3, s20, v5
	v_add3_u32 v21, v21, s0, v4
	v_mul_lo_u32 v26, s35, v3
	v_mad_u64_u32 v[4:5], s[24:25], s34, v3, 0
	v_or_b32_e32 v3, s20, v6
	v_add3_u32 v5, v5, s0, v26
	v_mul_lo_u32 v6, s35, v3
	v_mad_u64_u32 v[26:27], s[24:25], s34, v3, 0
	v_add3_u32 v27, v27, s0, v6
	v_lshl_add_u64 v[18:19], v[18:19], 2, s[28:29]
	v_lshlrev_b64 v[44:45], 2, v[186:187]
	v_lshl_add_u64 v[20:21], v[20:21], 2, s[28:29]
	v_lshl_add_u64 v[4:5], v[4:5], 2, s[28:29]
	v_lshl_add_u64 v[26:27], v[26:27], 2, s[28:29]
	v_lshl_add_u64 v[18:19], v[18:19], 0, v[44:45]
	v_lshl_add_u64 v[20:21], v[20:21], 0, v[44:45]
	v_lshl_add_u64 v[4:5], v[4:5], 0, v[44:45]
	v_lshl_add_u64 v[26:27], v[26:27], 0, v[44:45]
	v_or_b32_e32 v3, s20, v7
	global_load_dwordx4 v[22:25], v[18:19], off nt
	s_nop 0
	global_load_dwordx4 v[18:21], v[20:21], off nt
	s_nop 0
	global_load_dwordx4 v[30:33], v[4:5], off nt
	s_nop 0
	global_load_dwordx4 v[26:29], v[26:27], off nt
	v_mul_lo_u32 v6, s35, v3
	v_mad_u64_u32 v[4:5], s[24:25], s34, v3, 0
	v_or_b32_e32 v3, s20, v8
	v_add3_u32 v5, v5, s0, v6
	v_mul_lo_u32 v8, s35, v3
	v_mad_u64_u32 v[6:7], s[24:25], s34, v3, 0
	v_add3_u32 v7, v7, s0, v8
	v_lshl_add_u64 v[4:5], v[4:5], 2, s[28:29]
	v_lshl_add_u64 v[6:7], v[6:7], 2, s[28:29]
	v_lshl_add_u64 v[4:5], v[4:5], 0, v[44:45]
	v_lshl_add_u64 v[6:7], v[6:7], 0, v[44:45]
	v_or_b32_e32 v3, s20, v9
	global_load_dwordx4 v[38:41], v[4:5], off nt
	global_load_dwordx4 v[34:37], v[6:7], off nt
	v_mul_lo_u32 v6, s35, v3
	v_mad_u64_u32 v[4:5], s[24:25], s34, v3, 0
	v_or_b32_e32 v3, s20, v42
	v_add3_u32 v5, v5, s0, v6
	v_mul_lo_u32 v8, s35, v3
	v_mad_u64_u32 v[6:7], s[24:25], s34, v3, 0
	v_lshl_add_u64 v[4:5], v[4:5], 2, s[28:29]
	v_add3_u32 v7, v7, s0, v8
	v_lshl_add_u64 v[4:5], v[4:5], 0, v[44:45]
	v_lshl_add_u64 v[6:7], v[6:7], 2, s[28:29]
	v_lshl_add_u64 v[6:7], v[6:7], 0, v[44:45]
	global_load_dwordx4 v[46:49], v[4:5], off nt
	global_load_dwordx4 v[42:45], v[6:7], off nt
	s_cmp_lg_u64 s[30:31], 0
	s_cbranch_scc0 .LBB0_505
	s_lshl_b64 s[24:25], s[20:21], 2
	s_add_u32 s24, s30, s24
	s_addc_u32 s25, s31, s25
	global_load_dwordx4 v[6:9], v2, s[24:25] nt
	s_nop 0
	global_load_dwordx4 v[2:5], v2, s[24:25] offset:16 nt
	s_mov_b64 s[24:25], 0
	s_branch .LBB0_506

.LBB0_508:
	v_cndmask_b32_e64 v84, 0, 1.0, s[6:7]
	s_waitcnt vmcnt(15)
	v_pk_mul_f32 v[54:55], v[84:85], v[54:55] op_sel_hi:[0,1]
	s_waitcnt vmcnt(14)
	v_pk_mul_f32 v[88:89], v[84:85], v[50:51] op_sel_hi:[0,1]
	s_waitcnt vmcnt(13)
	v_pk_mul_f32 v[62:63], v[84:85], v[62:63] op_sel_hi:[0,1]
	s_waitcnt vmcnt(12)
	v_pk_mul_f32 v[58:59], v[84:85], v[58:59] op_sel_hi:[0,1]
	v_pk_mul_f32 v[86:87], v[84:85], v[52:53] op_sel_hi:[0,1]
	v_mov_b32_e32 v50, v54
	v_mov_b32_e32 v51, v88
	v_mov_b32_e32 v52, v62
	v_mov_b32_e32 v53, v58
	s_waitcnt vmcnt(11)
	v_pk_mul_f32 v[70:71], v[84:85], v[70:71] op_sel_hi:[0,1]
	s_waitcnt vmcnt(10)
	v_pk_mul_f32 v[66:67], v[84:85], v[66:67] op_sel_hi:[0,1]
	s_waitcnt vmcnt(9)
	v_pk_mul_f32 v[78:79], v[84:85], v[78:79] op_sel_hi:[0,1]
	s_waitcnt vmcnt(8)
	v_pk_mul_f32 v[74:75], v[84:85], v[74:75] op_sel_hi:[0,1]
	v_pk_mul_f32 v[50:51], v[50:51], v[10:11]
	v_pk_mul_f32 v[52:53], v[52:53], v[12:13]
	v_pk_mul_f32 v[56:57], v[84:85], v[56:57] op_sel_hi:[0,1]
	v_pk_mul_f32 v[64:65], v[84:85], v[64:65] op_sel_hi:[0,1]
	v_pk_mul_f32 v[60:61], v[84:85], v[60:61] op_sel_hi:[0,1]
	v_pk_mul_f32 v[72:73], v[84:85], v[72:73] op_sel_hi:[0,1]
	v_pk_mul_f32 v[68:69], v[84:85], v[68:69] op_sel_hi:[0,1]
	v_pk_mul_f32 v[80:81], v[84:85], v[80:81] op_sel_hi:[0,1]
	v_pk_mul_f32 v[76:77], v[84:85], v[76:77] op_sel_hi:[0,1]
	v_cvt_pk_bf16_f32 v50, v50, v51
	v_cvt_pk_bf16_f32 v51, v52, v53
	v_mov_b32_e32 v52, v70
	v_mov_b32_e32 v53, v66
	v_mov_b32_e32 v84, v78
	v_mov_b32_e32 v85, v74
	v_pk_mul_f32 v[52:53], v[52:53], v[14:15]
	v_pk_mul_f32 v[84:85], v[84:85], v[16:17]
	v_or_b32_e32 v54, s3, v1
	s_ashr_i32 s0, s3, 31
	v_cvt_pk_bf16_f32 v52, v52, v53
	v_cvt_pk_bf16_f32 v53, v84, v85
	v_mul_lo_u32 v58, s15, v54
	s_mul_i32 s0, s14, s0
	v_mad_u64_u32 v[84:85], s[6:7], s14, v54, 0
	v_add3_u32 v85, v85, s0, v58
	v_lshl_add_u64 v[84:85], v[84:85], 1, s[10:11]
	s_lshl_b64 s[6:7], s[12:13], 1
	v_lshl_add_u64 v[84:85], v[84:85], 0, s[6:7]
	v_lshlrev_b32_e32 v186, 1, v82
	v_lshl_add_u64 v[82:83], v[84:85], 0, v[186:187]
	v_mov_b32_e32 v88, v55
	global_store_dwordx4 v[82:83], v[50:53], off nt
	v_mov_b32_e32 v58, v63
	v_mov_b32_e32 v66, v71
	v_pk_mul_f32 v[50:51], v[88:89], v[10:11]
	v_mov_b32_e32 v74, v79
	v_cvt_pk_bf16_f32 v52, v50, v51
	v_pk_mul_f32 v[50:51], v[58:59], v[12:13]
	s_andn2_b64 vcc, exec, s[16:17]
	v_cvt_pk_bf16_f32 v53, v50, v51
	v_pk_mul_f32 v[50:51], v[66:67], v[14:15]
	s_nop 0
	v_cvt_pk_bf16_f32 v54, v50, v51
	v_pk_mul_f32 v[50:51], v[74:75], v[16:17]
	s_nop 0
	v_cvt_pk_bf16_f32 v55, v50, v51
	v_or_b32_e32 v50, 1, v1
	v_or_b32_e32 v51, s3, v50
	v_mul_lo_u32 v62, s15, v51
	v_mad_u64_u32 v[58:59], s[12:13], s14, v51, 0
	v_add3_u32 v59, v59, s0, v62
	v_lshl_add_u64 v[58:59], v[58:59], 1, s[10:11]
	v_lshl_add_u64 v[58:59], v[58:59], 0, s[6:7]
	v_lshl_add_u64 v[58:59], v[58:59], 0, v[186:187]
	global_store_dwordx4 v[58:59], v[52:55], off nt
	v_mov_b32_e32 v58, v80
	v_mov_b32_e32 v59, v76
	v_mov_b32_e32 v52, v56
	v_mov_b32_e32 v53, v86
	v_mov_b32_e32 v54, v64
	v_mov_b32_e32 v55, v60
	v_pk_mul_f32 v[52:53], v[52:53], v[10:11]
	v_pk_mul_f32 v[54:55], v[54:55], v[12:13]
	v_cvt_pk_bf16_f32 v52, v52, v53
	v_cvt_pk_bf16_f32 v53, v54, v55
	v_mov_b32_e32 v54, v72
	v_mov_b32_e32 v55, v68
	v_or_b32_e32 v51, 2, v1
	v_pk_mul_f32 v[54:55], v[54:55], v[14:15]
	v_pk_mul_f32 v[58:59], v[58:59], v[16:17]
	v_or_b32_e32 v56, s3, v51
	v_cvt_pk_bf16_f32 v54, v54, v55
	v_cvt_pk_bf16_f32 v55, v58, v59
	v_mul_lo_u32 v60, s15, v56
	v_mad_u64_u32 v[58:59], s[12:13], s14, v56, 0
	v_add3_u32 v59, v59, s0, v60
	v_lshl_add_u64 v[58:59], v[58:59], 1, s[10:11]
	v_lshl_add_u64 v[58:59], v[58:59], 0, s[6:7]
	v_mov_b32_e32 v86, v57
	v_lshl_add_u64 v[58:59], v[58:59], 0, v[186:187]
	v_pk_mul_f32 v[10:11], v[86:87], v[10:11]
	v_mov_b32_e32 v60, v65
	global_store_dwordx4 v[58:59], v[52:55], off nt
	v_mov_b32_e32 v68, v73
	v_mov_b32_e32 v76, v81
	v_cvt_pk_bf16_f32 v52, v10, v11
	v_pk_mul_f32 v[10:11], v[60:61], v[12:13]
	s_nop 0
	v_cvt_pk_bf16_f32 v53, v10, v11
	v_pk_mul_f32 v[10:11], v[68:69], v[14:15]
	s_nop 0
	v_cvt_pk_bf16_f32 v54, v10, v11
	v_pk_mul_f32 v[10:11], v[76:77], v[16:17]
	s_nop 0
	v_cvt_pk_bf16_f32 v55, v10, v11
	v_or_b32_e32 v10, 3, v1
	v_or_b32_e32 v11, s3, v10
	v_mul_lo_u32 v14, s15, v11
	v_mad_u64_u32 v[12:13], s[12:13], s14, v11, 0
	v_add3_u32 v13, v13, s0, v14
	v_lshl_add_u64 v[12:13], v[12:13], 1, s[10:11]
	v_lshl_add_u64 v[12:13], v[12:13], 0, s[6:7]
	v_lshl_add_u64 v[12:13], v[12:13], 0, v[186:187]
	global_store_dwordx4 v[12:13], v[52:55], off nt
	s_cbranch_vccnz .LBB0_510
	v_cndmask_b32_e64 v12, 0, 1.0, s[4:5]
	s_waitcnt vmcnt(11)
	v_pk_mul_f32 v[22:23], v[12:13], v[22:23] op_sel_hi:[0,1]
	s_waitcnt vmcnt(10)
	v_pk_mul_f32 v[18:19], v[12:13], v[18:19] op_sel_hi:[0,1]
	s_waitcnt vmcnt(9)
	v_pk_mul_f32 v[30:31], v[12:13], v[30:31] op_sel_hi:[0,1]
	s_waitcnt vmcnt(8)
	v_pk_mul_f32 v[26:27], v[12:13], v[26:27] op_sel_hi:[0,1]
	v_pk_mul_f32 v[16:17], v[12:13], v[24:25] op_sel_hi:[0,1]
	v_pk_mul_f32 v[20:21], v[12:13], v[20:21] op_sel_hi:[0,1]
	v_pk_mul_f32 v[24:25], v[12:13], v[32:33] op_sel_hi:[0,1]
	v_pk_mul_f32 v[28:29], v[12:13], v[28:29] op_sel_hi:[0,1]
	s_waitcnt vmcnt(7)
	v_pk_mul_f32 v[32:33], v[12:13], v[40:41] op_sel_hi:[0,1]
	v_pk_mul_f32 v[38:39], v[12:13], v[38:39] op_sel_hi:[0,1]
	s_waitcnt vmcnt(6)
	v_pk_mul_f32 v[36:37], v[12:13], v[36:37] op_sel_hi:[0,1]
	v_pk_mul_f32 v[34:35], v[12:13], v[34:35] op_sel_hi:[0,1]
	s_waitcnt vmcnt(5)
	v_pk_mul_f32 v[40:41], v[12:13], v[48:49] op_sel_hi:[0,1]
	v_pk_mul_f32 v[46:47], v[12:13], v[46:47] op_sel_hi:[0,1]
	s_waitcnt vmcnt(4)
	v_pk_mul_f32 v[44:45], v[12:13], v[44:45] op_sel_hi:[0,1]
	v_pk_mul_f32 v[42:43], v[12:13], v[42:43] op_sel_hi:[0,1]
	v_mov_b32_e32 v12, v22
	v_mov_b32_e32 v13, v18
	v_mov_b32_e32 v14, v30
	v_mov_b32_e32 v15, v26
	v_pk_mul_f32 v[12:13], v[12:13], v[6:7]
	v_pk_mul_f32 v[14:15], v[14:15], v[8:9]
	v_cvt_pk_bf16_f32 v12, v12, v13
	v_cvt_pk_bf16_f32 v13, v14, v15
	v_mov_b32_e32 v14, v38
	v_mov_b32_e32 v15, v34
	v_mov_b32_e32 v48, v46
	v_mov_b32_e32 v49, v42
	v_pk_mul_f32 v[14:15], v[14:15], v[2:3]
	v_pk_mul_f32 v[48:49], v[48:49], v[4:5]
	v_or_b32_e32 v1, s36, v1
	s_ashr_i32 s0, s36, 31
	v_cvt_pk_bf16_f32 v14, v14, v15
	v_cvt_pk_bf16_f32 v15, v48, v49
	v_mul_lo_u32 v11, s23, v1
	s_mul_i32 s0, s22, s0
	v_mad_u64_u32 v[48:49], s[4:5], s22, v1, 0
	v_add3_u32 v49, v49, s0, v11
	v_lshl_add_u64 v[48:49], v[48:49], 1, s[18:19]
	s_lshl_b64 s[4:5], s[20:21], 1
	v_lshl_add_u64 v[48:49], v[48:49], 0, s[4:5]
	v_lshl_add_u64 v[48:49], v[48:49], 0, v[186:187]
	v_mov_b32_e32 v18, v23
	v_mov_b32_e32 v26, v31
	global_store_dwordx4 v[48:49], v[12:15], off nt
	v_mov_b32_e32 v34, v39
	v_mov_b32_e32 v42, v47
	v_pk_mul_f32 v[12:13], v[18:19], v[6:7]
	v_pk_mul_f32 v[14:15], v[26:27], v[8:9]
	v_cvt_pk_bf16_f32 v12, v12, v13
	v_cvt_pk_bf16_f32 v13, v14, v15
	v_pk_mul_f32 v[14:15], v[34:35], v[2:3]
	v_pk_mul_f32 v[18:19], v[42:43], v[4:5]
	v_or_b32_e32 v1, s36, v50
	v_cvt_pk_bf16_f32 v14, v14, v15
	v_cvt_pk_bf16_f32 v15, v18, v19
	v_mul_lo_u32 v11, s23, v1
	v_mad_u64_u32 v[18:19], s[6:7], s22, v1, 0
	v_add3_u32 v19, v19, s0, v11
	v_lshl_add_u64 v[18:19], v[18:19], 1, s[18:19]
	v_lshl_add_u64 v[18:19], v[18:19], 0, s[4:5]
	v_lshl_add_u64 v[18:19], v[18:19], 0, v[186:187]
	global_store_dwordx4 v[18:19], v[12:15], off nt
	v_mov_b32_e32 v18, v40
	v_mov_b32_e32 v19, v44
	v_mov_b32_e32 v12, v16
	v_mov_b32_e32 v13, v20
	v_mov_b32_e32 v14, v24
	v_mov_b32_e32 v15, v28
	v_pk_mul_f32 v[12:13], v[12:13], v[6:7]
	v_pk_mul_f32 v[14:15], v[14:15], v[8:9]
	v_cvt_pk_bf16_f32 v12, v12, v13
	v_cvt_pk_bf16_f32 v13, v14, v15
	v_mov_b32_e32 v14, v32
	v_mov_b32_e32 v15, v36
	v_mov_b32_e32 v20, v17
	v_mov_b32_e32 v28, v25
	v_mov_b32_e32 v36, v33
	v_pk_mul_f32 v[14:15], v[14:15], v[2:3]
	v_pk_mul_f32 v[18:19], v[18:19], v[4:5]
	v_or_b32_e32 v1, s36, v51
	v_pk_mul_f32 v[6:7], v[20:21], v[6:7]
	v_pk_mul_f32 v[8:9], v[28:29], v[8:9]
	v_pk_mul_f32 v[2:3], v[36:37], v[2:3]
	v_mov_b32_e32 v44, v41
	v_cvt_pk_bf16_f32 v14, v14, v15
	v_cvt_pk_bf16_f32 v15, v18, v19
	v_mul_lo_u32 v11, s23, v1
	v_mad_u64_u32 v[18:19], s[6:7], s22, v1, 0
	v_cvt_pk_bf16_f32 v6, v6, v7
	v_cvt_pk_bf16_f32 v7, v8, v9
	v_cvt_pk_bf16_f32 v8, v2, v3
	v_pk_mul_f32 v[2:3], v[44:45], v[4:5]
	v_or_b32_e32 v1, s36, v10
	v_cvt_pk_bf16_f32 v9, v2, v3
	v_mul_lo_u32 v4, s23, v1
	v_mad_u64_u32 v[2:3], s[6:7], s22, v1, 0
	v_add3_u32 v19, v19, s0, v11
	v_add3_u32 v3, v3, s0, v4
	v_lshl_add_u64 v[18:19], v[18:19], 1, s[18:19]
	v_lshl_add_u64 v[2:3], v[2:3], 1, s[18:19]
	v_lshl_add_u64 v[18:19], v[18:19], 0, s[4:5]
	v_lshl_add_u64 v[2:3], v[2:3], 0, s[4:5]
	v_lshl_add_u64 v[18:19], v[18:19], 0, v[186:187]
	v_lshl_add_u64 v[2:3], v[2:3], 0, v[186:187]
	global_store_dwordx4 v[18:19], v[12:15], off nt
	global_store_dwordx4 v[2:3], v[6:9], off nt

.LBB0_676:
	v_and_b32_e32 v82, 56, v2
	v_cmp_lt_i32_e64 s[6:7], -1, v3
	v_and_b32_e32 v16, 63, v2
	v_or_b32_e32 v2, s12, v82
	s_ashr_i32 s13, s12, 31
	v_cndmask_b32_e64 v186, 0, v3, s[6:7]
	v_or_b32_e32 v3, 1, v82
	v_mul_lo_u32 v5, s27, v2
	s_mul_i32 s21, s26, s13
	v_mad_u64_u32 v[6:7], s[0:1], s26, v2, 0
	v_or_b32_e32 v2, s12, v3
	v_add3_u32 v7, v7, s21, v5
	v_mul_lo_u32 v5, s27, v2
	v_mad_u64_u32 v[8:9], s[0:1], s26, v2, 0
	v_add3_u32 v9, v9, s21, v5
	v_lshl_add_u64 v[6:7], v[6:7], 2, s[4:5]
	v_lshlrev_b64 v[10:11], 2, v[186:187]
	v_lshl_add_u64 v[8:9], v[8:9], 2, s[4:5]
	v_or_b32_e32 v5, 2, v82
	v_lshl_add_u64 v[6:7], v[6:7], 0, v[10:11]
	v_lshl_add_u64 v[8:9], v[8:9], 0, v[10:11]
	v_or_b32_e32 v2, s12, v5
	global_load_dwordx4 v[54:57], v[6:7], off nt
	global_load_dwordx4 v[50:53], v[8:9], off nt
	v_mul_lo_u32 v8, s27, v2
	v_mad_u64_u32 v[6:7], s[0:1], s26, v2, 0
	v_add3_u32 v7, v7, s21, v8
	v_lshl_add_u64 v[6:7], v[6:7], 2, s[4:5]
	v_lshl_add_u64 v[8:9], v[6:7], 0, v[10:11]
	v_or_b32_e32 v6, 3, v82
	v_or_b32_e32 v2, s12, v6
	v_mul_lo_u32 v7, s27, v2
	v_mad_u64_u32 v[12:13], s[0:1], s26, v2, 0
	v_add3_u32 v13, v13, s21, v7
	v_lshl_add_u64 v[12:13], v[12:13], 2, s[4:5]
	v_or_b32_e32 v7, 4, v82
	v_lshl_add_u64 v[12:13], v[12:13], 0, v[10:11]
	v_or_b32_e32 v2, s12, v7
	global_load_dwordx4 v[62:65], v[8:9], off nt
	global_load_dwordx4 v[58:61], v[12:13], off nt
	v_mul_lo_u32 v12, s27, v2
	v_mad_u64_u32 v[8:9], s[0:1], s26, v2, 0
	v_add3_u32 v9, v9, s21, v12
	v_lshl_add_u64 v[8:9], v[8:9], 2, s[4:5]
	v_lshl_add_u64 v[12:13], v[8:9], 0, v[10:11]
	v_or_b32_e32 v8, 5, v82
	v_or_b32_e32 v2, s12, v8
	v_mul_lo_u32 v9, s27, v2
	v_mad_u64_u32 v[14:15], s[0:1], s26, v2, 0
	v_add3_u32 v15, v15, s21, v9
	v_lshl_add_u64 v[14:15], v[14:15], 2, s[4:5]
	v_or_b32_e32 v9, 6, v82
	v_lshl_add_u64 v[14:15], v[14:15], 0, v[10:11]
	v_or_b32_e32 v2, s12, v9
	v_or_b32_e32 v42, 7, v16
	global_load_dwordx4 v[70:73], v[12:13], off nt
	global_load_dwordx4 v[66:69], v[14:15], off nt
	v_mul_lo_u32 v14, s27, v2
	v_mad_u64_u32 v[12:13], s[0:1], s26, v2, 0
	v_or_b32_e32 v2, s12, v42
	v_add3_u32 v13, v13, s21, v14
	v_mul_lo_u32 v16, s27, v2
	v_mad_u64_u32 v[14:15], s[0:1], s26, v2, 0
	v_lshl_add_u64 v[12:13], v[12:13], 2, s[4:5]
	v_add3_u32 v15, v15, s21, v16
	v_lshl_add_u64 v[12:13], v[12:13], 0, v[10:11]
	v_lshl_add_u64 v[14:15], v[14:15], 2, s[4:5]
	v_lshl_add_u64 v[10:11], v[14:15], 0, v[10:11]
	global_load_dwordx4 v[78:81], v[12:13], off nt
	global_load_dwordx4 v[74:77], v[10:11], off nt
	s_cmp_eq_u64 s[24:25], 0
	v_lshlrev_b32_e32 v2, 2, v82
	s_cbranch_scc1 .LBB0_678
	s_lshl_b64 s[0:1], s[12:13], 2
	s_add_u32 s0, s24, s0
	s_addc_u32 s1, s25, s1
	global_load_dwordx4 v[10:13], v2, s[0:1] nt
	global_load_dwordx4 v[14:17], v2, s[0:1] offset:16 nt
	s_branch .LBB0_679

.LBB0_679:
	v_or_b32_e32 v18, s20, v82
	s_ashr_i32 s21, s20, 31
	v_mul_lo_u32 v20, s35, v18
	s_mul_i32 s24, s34, s21
	v_mad_u64_u32 v[18:19], s[0:1], s34, v18, 0
	v_cmp_lt_i32_e64 s[4:5], -1, v4
	v_or_b32_e32 v3, s20, v3
	v_add3_u32 v19, v19, s24, v20
	v_cndmask_b32_e64 v186, 0, v4, s[4:5]
	v_mul_lo_u32 v4, s35, v3
	v_mad_u64_u32 v[20:21], s[0:1], s34, v3, 0
	v_or_b32_e32 v3, s20, v5
	v_add3_u32 v21, v21, s24, v4
	v_mul_lo_u32 v26, s35, v3
	v_mad_u64_u32 v[4:5], s[0:1], s34, v3, 0
	v_or_b32_e32 v3, s20, v6
	v_add3_u32 v5, v5, s24, v26
	v_mul_lo_u32 v6, s35, v3
	v_mad_u64_u32 v[26:27], s[0:1], s34, v3, 0
	v_add3_u32 v27, v27, s24, v6
	v_lshl_add_u64 v[18:19], v[18:19], 2, s[28:29]
	v_lshlrev_b64 v[44:45], 2, v[186:187]
	v_lshl_add_u64 v[20:21], v[20:21], 2, s[28:29]
	v_lshl_add_u64 v[4:5], v[4:5], 2, s[28:29]
	v_lshl_add_u64 v[26:27], v[26:27], 2, s[28:29]
	v_lshl_add_u64 v[18:19], v[18:19], 0, v[44:45]
	v_lshl_add_u64 v[20:21], v[20:21], 0, v[44:45]
	v_lshl_add_u64 v[4:5], v[4:5], 0, v[44:45]
	v_lshl_add_u64 v[26:27], v[26:27], 0, v[44:45]
	v_or_b32_e32 v3, s20, v7
	global_load_dwordx4 v[22:25], v[18:19], off nt
	s_nop 0
	global_load_dwordx4 v[18:21], v[20:21], off nt
	s_nop 0
	global_load_dwordx4 v[30:33], v[4:5], off nt
	s_nop 0
	global_load_dwordx4 v[26:29], v[26:27], off nt
	v_mul_lo_u32 v6, s35, v3
	v_mad_u64_u32 v[4:5], s[0:1], s34, v3, 0
	v_or_b32_e32 v3, s20, v8
	v_add3_u32 v5, v5, s24, v6
	v_mul_lo_u32 v8, s35, v3
	v_mad_u64_u32 v[6:7], s[0:1], s34, v3, 0
	v_add3_u32 v7, v7, s24, v8
	v_lshl_add_u64 v[4:5], v[4:5], 2, s[28:29]
	v_lshl_add_u64 v[6:7], v[6:7], 2, s[28:29]
	v_lshl_add_u64 v[4:5], v[4:5], 0, v[44:45]
	v_lshl_add_u64 v[6:7], v[6:7], 0, v[44:45]
	v_or_b32_e32 v3, s20, v9
	global_load_dwordx4 v[38:41], v[4:5], off nt
	global_load_dwordx4 v[34:37], v[6:7], off nt
	v_mul_lo_u32 v6, s35, v3
	v_mad_u64_u32 v[4:5], s[0:1], s34, v3, 0
	v_or_b32_e32 v3, s20, v42
	v_add3_u32 v5, v5, s24, v6
	v_mul_lo_u32 v8, s35, v3
	v_mad_u64_u32 v[6:7], s[0:1], s34, v3, 0
	v_lshl_add_u64 v[4:5], v[4:5], 2, s[28:29]
	v_add3_u32 v7, v7, s24, v8
	v_lshl_add_u64 v[4:5], v[4:5], 0, v[44:45]
	v_lshl_add_u64 v[6:7], v[6:7], 2, s[28:29]
	v_lshl_add_u64 v[6:7], v[6:7], 0, v[44:45]
	global_load_dwordx4 v[46:49], v[4:5], off nt
	global_load_dwordx4 v[42:45], v[6:7], off nt
	s_cmp_lg_u64 s[30:31], 0
	s_cbranch_scc0 .LBB0_681
	s_lshl_b64 s[0:1], s[20:21], 2
	s_add_u32 s0, s30, s0
	s_addc_u32 s1, s31, s1
	global_load_dwordx4 v[6:9], v2, s[0:1] nt
	s_nop 0
	global_load_dwordx4 v[2:5], v2, s[0:1] offset:16 nt
	s_mov_b64 s[24:25], 0
	s_branch .LBB0_682

.LBB0_684:
	v_cndmask_b32_e64 v84, 0, 1.0, s[6:7]
	s_waitcnt vmcnt(15)
	v_pk_mul_f32 v[54:55], v[84:85], v[54:55] op_sel_hi:[0,1]
	s_waitcnt vmcnt(14)
	v_pk_mul_f32 v[88:89], v[84:85], v[50:51] op_sel_hi:[0,1]
	s_waitcnt vmcnt(13)
	v_pk_mul_f32 v[62:63], v[84:85], v[62:63] op_sel_hi:[0,1]
	s_waitcnt vmcnt(12)
	v_pk_mul_f32 v[58:59], v[84:85], v[58:59] op_sel_hi:[0,1]
	v_pk_mul_f32 v[86:87], v[84:85], v[52:53] op_sel_hi:[0,1]
	v_mov_b32_e32 v50, v54
	v_mov_b32_e32 v51, v88
	v_mov_b32_e32 v52, v62
	v_mov_b32_e32 v53, v58
	s_waitcnt vmcnt(11)
	v_pk_mul_f32 v[70:71], v[84:85], v[70:71] op_sel_hi:[0,1]
	s_waitcnt vmcnt(10)
	v_pk_mul_f32 v[66:67], v[84:85], v[66:67] op_sel_hi:[0,1]
	s_waitcnt vmcnt(9)
	v_pk_mul_f32 v[78:79], v[84:85], v[78:79] op_sel_hi:[0,1]
	s_waitcnt vmcnt(8)
	v_pk_mul_f32 v[74:75], v[84:85], v[74:75] op_sel_hi:[0,1]
	v_pk_mul_f32 v[50:51], v[50:51], v[10:11]
	v_pk_mul_f32 v[52:53], v[52:53], v[12:13]
	v_pk_mul_f32 v[56:57], v[84:85], v[56:57] op_sel_hi:[0,1]
	v_pk_mul_f32 v[64:65], v[84:85], v[64:65] op_sel_hi:[0,1]
	v_pk_mul_f32 v[60:61], v[84:85], v[60:61] op_sel_hi:[0,1]
	v_pk_mul_f32 v[72:73], v[84:85], v[72:73] op_sel_hi:[0,1]
	v_pk_mul_f32 v[68:69], v[84:85], v[68:69] op_sel_hi:[0,1]
	v_pk_mul_f32 v[80:81], v[84:85], v[80:81] op_sel_hi:[0,1]
	v_pk_mul_f32 v[76:77], v[84:85], v[76:77] op_sel_hi:[0,1]
	v_cvt_pk_bf16_f32 v50, v50, v51
	v_cvt_pk_bf16_f32 v51, v52, v53
	v_mov_b32_e32 v52, v70
	v_mov_b32_e32 v53, v66
	v_mov_b32_e32 v84, v78
	v_mov_b32_e32 v85, v74
	v_pk_mul_f32 v[52:53], v[52:53], v[14:15]
	v_pk_mul_f32 v[84:85], v[84:85], v[16:17]
	v_or_b32_e32 v54, s3, v1
	s_ashr_i32 s0, s3, 31
	v_cvt_pk_bf16_f32 v52, v52, v53
	v_cvt_pk_bf16_f32 v53, v84, v85
	v_mul_lo_u32 v58, s15, v54
	s_mul_i32 s24, s14, s0
	v_mad_u64_u32 v[84:85], s[0:1], s14, v54, 0
	v_add3_u32 v85, v85, s24, v58
	v_lshl_add_u64 v[84:85], v[84:85], 1, s[10:11]
	s_lshl_b64 s[6:7], s[12:13], 1
	v_lshl_add_u64 v[84:85], v[84:85], 0, s[6:7]
	v_lshlrev_b32_e32 v186, 1, v82
	v_lshl_add_u64 v[82:83], v[84:85], 0, v[186:187]
	v_mov_b32_e32 v88, v55
	global_store_dwordx4 v[82:83], v[50:53], off nt
	v_mov_b32_e32 v58, v63
	v_mov_b32_e32 v66, v71
	v_pk_mul_f32 v[50:51], v[88:89], v[10:11]
	v_mov_b32_e32 v74, v79
	v_cvt_pk_bf16_f32 v52, v50, v51
	v_pk_mul_f32 v[50:51], v[58:59], v[12:13]
	s_andn2_b64 vcc, exec, s[16:17]
	v_cvt_pk_bf16_f32 v53, v50, v51
	v_pk_mul_f32 v[50:51], v[66:67], v[14:15]
	s_nop 0
	v_cvt_pk_bf16_f32 v54, v50, v51
	v_pk_mul_f32 v[50:51], v[74:75], v[16:17]
	s_nop 0
	v_cvt_pk_bf16_f32 v55, v50, v51
	v_or_b32_e32 v50, 1, v1
	v_or_b32_e32 v51, s3, v50
	v_mul_lo_u32 v62, s15, v51
	v_mad_u64_u32 v[58:59], s[0:1], s14, v51, 0
	v_add3_u32 v59, v59, s24, v62
	v_lshl_add_u64 v[58:59], v[58:59], 1, s[10:11]
	v_lshl_add_u64 v[58:59], v[58:59], 0, s[6:7]
	v_lshl_add_u64 v[58:59], v[58:59], 0, v[186:187]
	global_store_dwordx4 v[58:59], v[52:55], off nt
	v_mov_b32_e32 v58, v80
	v_mov_b32_e32 v59, v76
	v_mov_b32_e32 v52, v56
	v_mov_b32_e32 v53, v86
	v_mov_b32_e32 v54, v64
	v_mov_b32_e32 v55, v60
	v_pk_mul_f32 v[52:53], v[52:53], v[10:11]
	v_pk_mul_f32 v[54:55], v[54:55], v[12:13]
	v_cvt_pk_bf16_f32 v52, v52, v53
	v_cvt_pk_bf16_f32 v53, v54, v55
	v_mov_b32_e32 v54, v72
	v_mov_b32_e32 v55, v68
	v_or_b32_e32 v51, 2, v1
	v_pk_mul_f32 v[54:55], v[54:55], v[14:15]
	v_pk_mul_f32 v[58:59], v[58:59], v[16:17]
	v_or_b32_e32 v56, s3, v51
	v_cvt_pk_bf16_f32 v54, v54, v55
	v_cvt_pk_bf16_f32 v55, v58, v59
	v_mul_lo_u32 v60, s15, v56
	v_mad_u64_u32 v[58:59], s[0:1], s14, v56, 0
	v_add3_u32 v59, v59, s24, v60
	v_lshl_add_u64 v[58:59], v[58:59], 1, s[10:11]
	v_lshl_add_u64 v[58:59], v[58:59], 0, s[6:7]
	v_mov_b32_e32 v86, v57
	v_lshl_add_u64 v[58:59], v[58:59], 0, v[186:187]
	v_pk_mul_f32 v[10:11], v[86:87], v[10:11]
	v_mov_b32_e32 v60, v65
	global_store_dwordx4 v[58:59], v[52:55], off nt
	v_mov_b32_e32 v68, v73
	v_mov_b32_e32 v76, v81
	v_cvt_pk_bf16_f32 v52, v10, v11
	v_pk_mul_f32 v[10:11], v[60:61], v[12:13]
	s_nop 0
	v_cvt_pk_bf16_f32 v53, v10, v11
	v_pk_mul_f32 v[10:11], v[68:69], v[14:15]
	s_nop 0
	v_cvt_pk_bf16_f32 v54, v10, v11
	v_pk_mul_f32 v[10:11], v[76:77], v[16:17]
	s_nop 0
	v_cvt_pk_bf16_f32 v55, v10, v11
	v_or_b32_e32 v10, 3, v1
	v_or_b32_e32 v11, s3, v10
	v_mul_lo_u32 v14, s15, v11
	v_mad_u64_u32 v[12:13], s[0:1], s14, v11, 0
	v_add3_u32 v13, v13, s24, v14
	v_lshl_add_u64 v[12:13], v[12:13], 1, s[10:11]
	v_lshl_add_u64 v[12:13], v[12:13], 0, s[6:7]
	v_lshl_add_u64 v[12:13], v[12:13], 0, v[186:187]
	global_store_dwordx4 v[12:13], v[52:55], off nt
	s_cbranch_vccnz .LBB0_686
	v_cndmask_b32_e64 v12, 0, 1.0, s[4:5]
	s_waitcnt vmcnt(11)
	v_pk_mul_f32 v[22:23], v[12:13], v[22:23] op_sel_hi:[0,1]
	s_waitcnt vmcnt(10)
	v_pk_mul_f32 v[18:19], v[12:13], v[18:19] op_sel_hi:[0,1]
	s_waitcnt vmcnt(9)
	v_pk_mul_f32 v[30:31], v[12:13], v[30:31] op_sel_hi:[0,1]
	s_waitcnt vmcnt(8)
	v_pk_mul_f32 v[26:27], v[12:13], v[26:27] op_sel_hi:[0,1]
	v_pk_mul_f32 v[16:17], v[12:13], v[24:25] op_sel_hi:[0,1]
	v_pk_mul_f32 v[20:21], v[12:13], v[20:21] op_sel_hi:[0,1]
	v_pk_mul_f32 v[24:25], v[12:13], v[32:33] op_sel_hi:[0,1]
	v_pk_mul_f32 v[28:29], v[12:13], v[28:29] op_sel_hi:[0,1]
	s_waitcnt vmcnt(7)
	v_pk_mul_f32 v[32:33], v[12:13], v[40:41] op_sel_hi:[0,1]
	v_pk_mul_f32 v[38:39], v[12:13], v[38:39] op_sel_hi:[0,1]
	s_waitcnt vmcnt(6)
	v_pk_mul_f32 v[36:37], v[12:13], v[36:37] op_sel_hi:[0,1]
	v_pk_mul_f32 v[34:35], v[12:13], v[34:35] op_sel_hi:[0,1]
	s_waitcnt vmcnt(5)
	v_pk_mul_f32 v[40:41], v[12:13], v[48:49] op_sel_hi:[0,1]
	v_pk_mul_f32 v[46:47], v[12:13], v[46:47] op_sel_hi:[0,1]
	s_waitcnt vmcnt(4)
	v_pk_mul_f32 v[44:45], v[12:13], v[44:45] op_sel_hi:[0,1]
	v_pk_mul_f32 v[42:43], v[12:13], v[42:43] op_sel_hi:[0,1]
	v_mov_b32_e32 v12, v22
	v_mov_b32_e32 v13, v18
	v_mov_b32_e32 v14, v30
	v_mov_b32_e32 v15, v26
	v_pk_mul_f32 v[12:13], v[12:13], v[6:7]
	v_pk_mul_f32 v[14:15], v[14:15], v[8:9]
	v_cvt_pk_bf16_f32 v12, v12, v13
	v_cvt_pk_bf16_f32 v13, v14, v15
	v_mov_b32_e32 v14, v38
	v_mov_b32_e32 v15, v34
	v_mov_b32_e32 v48, v46
	v_mov_b32_e32 v49, v42
	v_pk_mul_f32 v[14:15], v[14:15], v[2:3]
	v_pk_mul_f32 v[48:49], v[48:49], v[4:5]
	v_or_b32_e32 v1, s36, v1
	s_ashr_i32 s0, s36, 31
	v_cvt_pk_bf16_f32 v14, v14, v15
	v_cvt_pk_bf16_f32 v15, v48, v49
	v_mul_lo_u32 v11, s23, v1
	s_mul_i32 s3, s22, s0
	v_mad_u64_u32 v[48:49], s[0:1], s22, v1, 0
	v_add3_u32 v49, v49, s3, v11
	v_lshl_add_u64 v[48:49], v[48:49], 1, s[18:19]
	s_lshl_b64 s[4:5], s[20:21], 1
	v_lshl_add_u64 v[48:49], v[48:49], 0, s[4:5]
	v_lshl_add_u64 v[48:49], v[48:49], 0, v[186:187]
	v_mov_b32_e32 v18, v23
	v_mov_b32_e32 v26, v31
	global_store_dwordx4 v[48:49], v[12:15], off nt
	v_mov_b32_e32 v34, v39
	v_mov_b32_e32 v42, v47
	v_pk_mul_f32 v[12:13], v[18:19], v[6:7]
	v_pk_mul_f32 v[14:15], v[26:27], v[8:9]
	v_cvt_pk_bf16_f32 v12, v12, v13
	v_cvt_pk_bf16_f32 v13, v14, v15
	v_pk_mul_f32 v[14:15], v[34:35], v[2:3]
	v_pk_mul_f32 v[18:19], v[42:43], v[4:5]
	v_or_b32_e32 v1, s36, v50
	v_cvt_pk_bf16_f32 v14, v14, v15
	v_cvt_pk_bf16_f32 v15, v18, v19
	v_mul_lo_u32 v11, s23, v1
	v_mad_u64_u32 v[18:19], s[0:1], s22, v1, 0
	v_add3_u32 v19, v19, s3, v11
	v_lshl_add_u64 v[18:19], v[18:19], 1, s[18:19]
	v_lshl_add_u64 v[18:19], v[18:19], 0, s[4:5]
	v_lshl_add_u64 v[18:19], v[18:19], 0, v[186:187]
	global_store_dwordx4 v[18:19], v[12:15], off nt
	v_mov_b32_e32 v18, v40
	v_mov_b32_e32 v19, v44
	v_mov_b32_e32 v12, v16
	v_mov_b32_e32 v13, v20
	v_mov_b32_e32 v14, v24
	v_mov_b32_e32 v15, v28
	v_pk_mul_f32 v[12:13], v[12:13], v[6:7]
	v_pk_mul_f32 v[14:15], v[14:15], v[8:9]
	v_cvt_pk_bf16_f32 v12, v12, v13
	v_cvt_pk_bf16_f32 v13, v14, v15
	v_mov_b32_e32 v14, v32
	v_mov_b32_e32 v15, v36
	v_mov_b32_e32 v20, v17
	v_mov_b32_e32 v28, v25
	v_mov_b32_e32 v36, v33
	v_pk_mul_f32 v[14:15], v[14:15], v[2:3]
	v_pk_mul_f32 v[18:19], v[18:19], v[4:5]
	v_or_b32_e32 v1, s36, v51
	v_pk_mul_f32 v[6:7], v[20:21], v[6:7]
	v_pk_mul_f32 v[8:9], v[28:29], v[8:9]
	v_pk_mul_f32 v[2:3], v[36:37], v[2:3]
	v_mov_b32_e32 v44, v41
	v_cvt_pk_bf16_f32 v14, v14, v15
	v_cvt_pk_bf16_f32 v15, v18, v19
	v_mul_lo_u32 v11, s23, v1
	v_mad_u64_u32 v[18:19], s[0:1], s22, v1, 0
	v_cvt_pk_bf16_f32 v6, v6, v7
	v_cvt_pk_bf16_f32 v7, v8, v9
	v_cvt_pk_bf16_f32 v8, v2, v3
	v_pk_mul_f32 v[2:3], v[44:45], v[4:5]
	v_or_b32_e32 v1, s36, v10
	v_cvt_pk_bf16_f32 v9, v2, v3
	v_mul_lo_u32 v4, s23, v1
	v_mad_u64_u32 v[2:3], s[0:1], s22, v1, 0
	v_add3_u32 v19, v19, s3, v11
	v_add3_u32 v3, v3, s3, v4
	v_lshl_add_u64 v[18:19], v[18:19], 1, s[18:19]
	v_lshl_add_u64 v[2:3], v[2:3], 1, s[18:19]
	v_lshl_add_u64 v[18:19], v[18:19], 0, s[4:5]
	v_lshl_add_u64 v[2:3], v[2:3], 0, s[4:5]
	v_lshl_add_u64 v[18:19], v[18:19], 0, v[186:187]
	v_lshl_add_u64 v[2:3], v[2:3], 0, v[186:187]
	global_store_dwordx4 v[18:19], v[12:15], off nt
	global_store_dwordx4 v[2:3], v[6:9], off nt
